# hgrn_pre: second lower-bound parameter pair loaded up front (one exposed load latency less per item)
# speedup vs baseline: 1.0034x; 1.0034x over previous
.LBB0_413:
	s_lshl_b32 s0, s89, 7
	s_and_b32 s12, s0, 0x380
	s_lshl_b32 s0, s12, 2
	v_lshl_add_u64 v[0:1], v[134:135], 0, s[0:1]
	s_waitcnt lgkmcnt(1)
	v_add_co_u32_e32 v2, vcc, 0x1000, v0
	s_movk_i32 s63, 0x3000
	s_waitcnt lgkmcnt(0)
	v_addc_co_u32_e32 v3, vcc, 0, v1, vcc
	global_load_dwordx2 v[2:3], v[2:3], off
	s_nop 0
	global_load_dwordx2 v[4:5], v[0:1], off
	v_add_co_u32_e32 v252, vcc, 0x3000, v0
	s_nop 1
	v_addc_co_u32_e32 v253, vcc, 0, v1, vcc
	v_add_co_u32_e32 v254, vcc, 0x2000, v0
	s_nop 1
	v_addc_co_u32_e32 v255, vcc, 0, v1, vcc
	global_load_dwordx2 v[252:253], v[252:253], off
	global_load_dwordx2 v[254:255], v[254:255], off
	s_movk_i32 s62, 0x2000
	s_ashr_i32 s56, s89, 9
	v_readfirstlane_b32 s9, v221
	s_bfe_u32 s8, s89, 0x60003
	s_ashr_i32 s57, s56, 31
	s_lshr_b32 s14, s9, 6
	s_lshl_b64 s[18:19], s[56:57], 12
	s_lshl_b32 s13, s8, 6
	s_or_b32 s13, s18, s13
	s_lshl_b32 s15, s14, 3
	s_add_u32 s54, s13, s15
	s_addc_u32 s55, s19, 0
	s_mul_i32 s13, s55, 0x4800
	s_mul_hi_u32 s15, s54, 0x4800
	s_add_i32 s15, s15, s13
	s_mul_i32 s13, s54, 0x4800
	s_add_u32 s13, s82, s13
	s_addc_u32 s15, s83, s15
	s_lshl_b32 s12, s12, 1
	s_add_u32 s58, s13, s12
	s_addc_u32 s59, s15, 0
	v_lshlrev_b32_e32 v128, 1, v132
	s_movk_i32 s13, 0x4000
	global_load_dword v50, v128, s[58:59] nt
	s_cmp_lt_u32 s9, 64
	s_cselect_b64 s[50:51], -1, 0
	s_cmpk_gt_u32 s9, 0x7f
	s_cselect_b64 s[52:53], -1, 0
	s_cmpk_gt_u32 s9, 0xbf
	s_cselect_b64 s[48:49], -1, 0
	s_cmpk_lt_u32 s9, 0x80
	s_cselect_b64 s[46:47], -1, 0
	s_cmpk_gt_u32 s9, 0xff
	s_cselect_b64 s[44:45], -1, 0
	s_cmpk_lt_u32 s9, 0xc0
	s_cselect_b64 s[42:43], -1, 0
	s_cmpk_gt_u32 s9, 0x13f
	s_cselect_b64 s[40:41], -1, 0
	s_cmpk_lt_u32 s9, 0x100
	s_cselect_b64 s[38:39], -1, 0
	s_cmpk_gt_u32 s9, 0x17f
	s_cselect_b64 s[36:37], -1, 0
	s_cmpk_lt_u32 s9, 0x140
	s_cselect_b64 s[34:35], -1, 0
	s_cmpk_gt_u32 s9, 0x1bf
	s_cselect_b64 s[30:31], -1, 0
	s_cmpk_lt_u32 s9, 0x180
	s_cselect_b64 s[28:29], -1, 0
	s_cmpk_gt_u32 s9, 0x1ff
	s_cselect_b64 s[26:27], -1, 0
	s_cmpk_lt_u32 s9, 0x1c0
	s_cselect_b64 s[24:25], -1, 0
	s_movk_i32 s86, 0x2000
	s_movk_i32 s96, 0x3000
	s_waitcnt vmcnt(1)
	v_sub_f32_e32 v2, v2, v4
	v_mul_f32_e32 v4, 0x3fb8aa3b, v2
	v_fma_f32 v6, v2, s11, -v4
	v_rndne_f32_e32 v7, v4
	v_fmac_f32_e32 v6, 0x32a5705f, v2
	v_sub_f32_e32 v4, v4, v7
	v_add_f32_e32 v4, v4, v6
	v_exp_f32_e32 v4, v4
	v_cvt_i32_f32_e32 v6, v7
	v_cmp_ngt_f32_e32 vcc, s16, v2
	v_ldexp_f32 v4, v4, v6
	s_nop 0
	v_cndmask_b32_e32 v4, 0, v4, vcc
	v_cmp_nlt_f32_e32 vcc, s17, v2
	v_sub_f32_e32 v2, v3, v5
	v_mul_f32_e32 v3, 0x3fb8aa3b, v2
	v_cndmask_b32_e32 v52, v222, v4, vcc
	v_fma_f32 v4, v2, s11, -v3
	v_rndne_f32_e32 v5, v3
	v_fmac_f32_e32 v4, 0x32a5705f, v2
	v_sub_f32_e32 v3, v3, v5
	v_add_f32_e32 v3, v3, v4
	v_exp_f32_e32 v3, v3
	v_cvt_i32_f32_e32 v4, v5
	v_cmp_ngt_f32_e32 vcc, s16, v2
	s_waitcnt vmcnt(0)
	v_lshlrev_b32_e32 v66, 16, v50
	v_and_b32_e32 v67, 0xffff0000, v50
	v_ldexp_f32 v3, v3, v4
	v_cndmask_b32_e32 v3, 0, v3, vcc
	v_cmp_nlt_f32_e32 vcc, s17, v2
	v_mul_f32_e32 v50, 0xbfb8aa3b, v66
	v_exp_f32_e32 v50, v50
	v_cndmask_b32_e32 v53, v222, v3, vcc
	v_add_f32_e32 v50, 1.0, v50
	v_rcp_f32_e32 v50, v50
	v_pk_add_f32 v[52:53], v[52:53], 1.0 op_sel_hi:[1,0]
	v_mov_b32_e32 v2, v252
	v_mov_b32_e32 v3, v253
	v_mov_b32_e32 v0, v254
	v_mov_b32_e32 v1, v255
	v_sub_f32_e32 v0, v2, v0
	v_mul_f32_e32 v2, 0x3fb8aa3b, v0
	v_fma_f32 v4, v0, s11, -v2
	v_rndne_f32_e32 v5, v2
	v_fmac_f32_e32 v4, 0x32a5705f, v0
	v_sub_f32_e32 v2, v2, v5
	v_add_f32_e32 v2, v2, v4
	v_exp_f32_e32 v2, v2
	v_cvt_i32_f32_e32 v4, v5
	v_cmp_ngt_f32_e32 vcc, s16, v0
	v_ldexp_f32 v2, v2, v4
	s_nop 0
	v_cndmask_b32_e32 v2, 0, v2, vcc
	v_cmp_nlt_f32_e32 vcc, s17, v0
	v_sub_f32_e32 v0, v3, v1
	v_mul_f32_e32 v1, 0x3fb8aa3b, v0
	v_cndmask_b32_e32 v56, v222, v2, vcc
	v_fma_f32 v2, v0, s11, -v1
	v_rndne_f32_e32 v3, v1
	v_fmac_f32_e32 v2, 0x32a5705f, v0
	v_sub_f32_e32 v1, v1, v3
	v_add_f32_e32 v1, v1, v2
	v_exp_f32_e32 v1, v1
	v_cvt_i32_f32_e32 v2, v3
	v_cmp_ngt_f32_e32 vcc, s16, v0
	v_ldexp_f32 v1, v1, v2
	s_nop 0
	v_cndmask_b32_e32 v1, 0, v1, vcc
	v_cmp_nlt_f32_e32 vcc, s17, v0
	s_nop 1
	v_cndmask_b32_e32 v57, v222, v1, vcc
	v_lshl_add_u64 v[0:1], s[58:59], 0, v[128:129]
	v_add_co_u32_e32 v44, vcc, s7, v0
	v_pk_add_f32 v[56:57], v[56:57], 1.0 op_sel_hi:[1,0]
	s_nop 0
	v_addc_co_u32_e32 v45, vcc, 0, v1, vcc
	global_load_dword v2, v[44:45], off offset:2048 nt
	v_add_co_u32_e32 v42, vcc, s62, v0
	s_nop 1
	v_addc_co_u32_e32 v43, vcc, 0, v1, vcc
	v_add_co_u32_e32 v40, vcc, s13, v0
	s_movk_i32 s13, 0x6000
	s_nop 0
	v_addc_co_u32_e32 v41, vcc, 0, v1, vcc
	v_add_co_u32_e32 v38, vcc, s13, v0
	global_load_dword v46, v[42:43], off nt
	global_load_dword v64, v[40:41], off offset:2048 nt
	v_addc_co_u32_e32 v39, vcc, 0, v1, vcc
	global_load_dword v3, v[38:39], off nt
	global_load_dword v48, v[38:39], off offset:2048 nt
	v_add_co_u32_e32 v36, vcc, s33, v0
	s_mov_b32 s13, 0xa000
	s_nop 0
	v_addc_co_u32_e32 v37, vcc, 0, v1, vcc
	v_add_co_u32_e32 v34, vcc, s13, v0
	global_load_dword v72, v[36:37], off nt
	s_nop 0
	v_addc_co_u32_e32 v35, vcc, 0, v1, vcc
	global_load_dword v4, v[34:35], off offset:2048 nt
	s_mov_b32 s13, 0xb000
	v_add_co_u32_e32 v30, vcc, s13, v0
	s_mov_b32 s13, 0xd000
	s_nop 0
	v_addc_co_u32_e32 v31, vcc, 0, v1, vcc
	v_add_co_u32_e32 v32, vcc, s13, v0
	s_mov_b32 s13, 0xf000
	s_nop 0
	v_addc_co_u32_e32 v33, vcc, 0, v1, vcc
	v_add_co_u32_e32 v28, vcc, s13, v0
	global_load_dword v49, v[30:31], off nt
	global_load_dword v80, v[32:33], off offset:2048 nt
	v_addc_co_u32_e32 v29, vcc, 0, v1, vcc
	global_load_dword v5, v[28:29], off nt
	global_load_dword v51, v[28:29], off offset:2048 nt
	s_mov_b32 s13, 0x12000
	v_add_co_u32_e32 v26, vcc, s13, v0
	s_mov_b32 s13, 0x13000
	s_nop 0
	v_addc_co_u32_e32 v27, vcc, 0, v1, vcc
	v_add_co_u32_e32 v24, vcc, s13, v0
	global_load_dword v88, v[26:27], off nt
	s_nop 0
	v_addc_co_u32_e32 v25, vcc, 0, v1, vcc
	global_load_dword v6, v[24:25], off offset:2048 nt
	s_mov_b32 s13, 0x14000
	v_add_co_u32_e32 v22, vcc, s13, v0
	s_mov_b32 s13, 0x16000
	s_nop 0
	v_addc_co_u32_e32 v23, vcc, 0, v1, vcc
	v_add_co_u32_e32 v20, vcc, s13, v0
	s_mov_b32 s13, 0x18000
	s_nop 0
	v_addc_co_u32_e32 v21, vcc, 0, v1, vcc
	v_add_co_u32_e32 v16, vcc, s13, v0
	global_load_dword v58, v[22:23], off nt
	global_load_dword v96, v[20:21], off offset:2048 nt
	v_addc_co_u32_e32 v17, vcc, 0, v1, vcc
	global_load_dword v7, v[16:17], off nt
	global_load_dword v59, v[16:17], off offset:2048 nt
	s_mov_b32 s13, 0x1b000
	v_add_co_u32_e32 v18, vcc, s13, v0
	s_mov_b32 s13, 0x1c000
	s_nop 0
	v_addc_co_u32_e32 v19, vcc, 0, v1, vcc
	v_add_co_u32_e32 v14, vcc, s13, v0
	global_load_dword v100, v[18:19], off nt
	s_nop 0
	v_addc_co_u32_e32 v15, vcc, 0, v1, vcc
	global_load_dword v62, v[14:15], off offset:2048 nt
	s_waitcnt vmcnt(18)
	v_lshlrev_b32_e32 v54, 16, v2
	v_and_b32_e32 v2, 0xffff0000, v2
	v_mul_f32_e32 v2, 0xbfb8aa3b, v2
	v_exp_f32_e32 v2, v2
	s_mov_b32 s13, 0x1d000
	v_add_co_u32_e32 v12, vcc, s13, v0
	v_add_f32_e32 v2, 1.0, v2
	v_rcp_f32_e32 v55, v2
	s_waitcnt vmcnt(15)
	v_lshlrev_b32_e32 v2, 16, v3
	v_mul_f32_e32 v2, 0xbfb8aa3b, v2
	v_exp_f32_e32 v2, v2
	v_addc_co_u32_e32 v13, vcc, 0, v1, vcc
	global_load_dword v63, v[12:13], off nt
	v_add_f32_e32 v2, 1.0, v2
	v_rcp_f32_e32 v60, v2
	v_and_b32_e32 v2, 0xffff0000, v3
	v_mul_f32_e32 v2, 0xbfb8aa3b, v2
	v_exp_f32_e32 v2, v2
	s_mov_b32 s13, 0x1f000
	v_add_co_u32_e32 v10, vcc, s13, v0
	v_add_f32_e32 v2, 1.0, v2
	v_rcp_f32_e32 v61, v2
	s_waitcnt vmcnt(13)
	v_lshlrev_b32_e32 v2, 16, v4
	v_mul_f32_e32 v2, 0xbfb8aa3b, v2
	v_exp_f32_e32 v2, v2
	v_addc_co_u32_e32 v11, vcc, 0, v1, vcc
	global_load_dword v47, v[10:11], off offset:2048 nt
	v_add_f32_e32 v2, 1.0, v2
	v_rcp_f32_e32 v68, v2
	v_and_b32_e32 v2, 0xffff0000, v4
	v_mul_f32_e32 v2, 0xbfb8aa3b, v2
	v_exp_f32_e32 v2, v2
	s_mov_b32 s13, 0x21000
	v_add_co_u32_e32 v8, vcc, s13, v0
	v_add_f32_e32 v2, 1.0, v2
	v_rcp_f32_e32 v69, v2
	s_waitcnt vmcnt(11)
	v_lshlrev_b32_e32 v2, 16, v5
	v_mul_f32_e32 v2, 0xbfb8aa3b, v2
	v_exp_f32_e32 v2, v2
	v_readlane_b32 s13, v251, 45
	v_addc_co_u32_e32 v9, vcc, 0, v1, vcc
	v_add_f32_e32 v2, 1.0, v2
	v_rcp_f32_e32 v76, v2
	v_and_b32_e32 v2, 0xffff0000, v5
	v_mul_f32_e32 v2, 0xbfb8aa3b, v2
	v_exp_f32_e32 v2, v2
	v_mul_f32_e32 v54, 0xbfb8aa3b, v54
	v_exp_f32_e32 v54, v54
	global_load_dword v0, v[8:9], off nt
	global_load_dword v1, v[8:9], off offset:2048 nt
	v_add_f32_e32 v2, 1.0, v2
	v_rcp_f32_e32 v77, v2
	s_waitcnt vmcnt(10)
	v_lshlrev_b32_e32 v2, 16, v6
	v_mul_f32_e32 v2, 0xbfb8aa3b, v2
	v_exp_f32_e32 v2, v2
	v_add_f32_e32 v54, 1.0, v54
	v_rcp_f32_e32 v54, v54
	v_add_f32_e32 v2, 1.0, v2
	v_rcp_f32_e32 v84, v2
	v_and_b32_e32 v2, 0xffff0000, v6
	v_mul_f32_e32 v2, 0xbfb8aa3b, v2
	v_exp_f32_e32 v2, v2
	s_waitcnt vmcnt(3)
	v_lshlrev_b32_e32 v6, 16, v63
	v_add_f32_e32 v2, 1.0, v2
	v_rcp_f32_e32 v85, v2
	v_lshlrev_b32_e32 v2, 16, v7
	v_mul_f32_e32 v2, 0xbfb8aa3b, v2
	v_exp_f32_e32 v2, v2
	v_mul_f32_e32 v6, 0xbfb8aa3b, v6
	v_exp_f32_e32 v6, v6
	v_add_f32_e32 v2, 1.0, v2
	v_rcp_f32_e32 v92, v2
	v_and_b32_e32 v2, 0xffff0000, v7
	v_mul_f32_e32 v2, 0xbfb8aa3b, v2
	v_exp_f32_e32 v2, v2
	v_and_b32_e32 v7, 0xffff0000, v63
	v_mul_f32_e32 v7, 0xbfb8aa3b, v7
	v_exp_f32_e32 v7, v7
	v_add_f32_e32 v2, 1.0, v2
	v_rcp_f32_e32 v93, v2
	v_lshlrev_b32_e32 v2, 16, v62
	v_mul_f32_e32 v2, 0xbfb8aa3b, v2
	v_exp_f32_e32 v2, v2
	v_add_f32_e32 v6, 1.0, v6
	v_add_f32_e32 v7, 1.0, v7
	v_rcp_f32_e32 v6, v6
	v_add_f32_e32 v2, 1.0, v2
	v_rcp_f32_e32 v4, v2
	v_and_b32_e32 v2, 0xffff0000, v62
	v_lshlrev_b32_e32 v62, 16, v59
	v_and_b32_e32 v59, 0xffff0000, v59
	v_mul_f32_e32 v59, 0xbfb8aa3b, v59
	v_exp_f32_e32 v59, v59
	v_mul_f32_e32 v62, 0xbfb8aa3b, v62
	v_exp_f32_e32 v62, v62
	v_mul_f32_e32 v2, 0xbfb8aa3b, v2
	v_add_f32_e32 v59, 1.0, v59
	v_rcp_f32_e32 v95, v59
	v_lshlrev_b32_e32 v59, 16, v58
	v_and_b32_e32 v58, 0xffff0000, v58
	v_mul_f32_e32 v58, 0xbfb8aa3b, v58
	v_exp_f32_e32 v58, v58
	v_mul_f32_e32 v59, 0xbfb8aa3b, v59
	v_exp_f32_e32 v59, v59
	v_add_f32_e32 v62, 1.0, v62
	v_add_f32_e32 v58, 1.0, v58
	v_rcp_f32_e32 v87, v58
	v_lshlrev_b32_e32 v58, 16, v51
	v_and_b32_e32 v51, 0xffff0000, v51
	v_mul_f32_e32 v51, 0xbfb8aa3b, v51
	v_exp_f32_e32 v51, v51
	v_mul_f32_e32 v58, 0xbfb8aa3b, v58
	v_exp_f32_e32 v58, v58
	v_add_f32_e32 v59, 1.0, v59
	v_add_f32_e32 v51, 1.0, v51
	v_rcp_f32_e32 v79, v51
	v_lshlrev_b32_e32 v51, 16, v49
	v_and_b32_e32 v49, 0xffff0000, v49
	v_mul_f32_e32 v49, 0xbfb8aa3b, v49
	v_exp_f32_e32 v49, v49
	v_mul_f32_e32 v51, 0xbfb8aa3b, v51
	v_exp_f32_e32 v51, v51
	v_rcp_f32_e32 v86, v59
	v_add_f32_e32 v49, 1.0, v49
	v_rcp_f32_e32 v71, v49
	v_lshlrev_b32_e32 v49, 16, v48
	v_and_b32_e32 v48, 0xffff0000, v48
	v_mul_f32_e32 v48, 0xbfb8aa3b, v48
	v_exp_f32_e32 v48, v48
	v_add_f32_e32 v51, 1.0, v51
	v_rcp_f32_e32 v70, v51
	v_mul_f32_e32 v51, 0xbfb8aa3b, v67
	v_add_f32_e32 v48, 1.0, v48
	v_rcp_f32_e32 v63, v48
	v_lshlrev_b32_e32 v48, 16, v46
	v_and_b32_e32 v46, 0xffff0000, v46
	v_mul_f32_e32 v46, 0xbfb8aa3b, v46
	v_mul_f32_e32 v48, 0xbfb8aa3b, v48
	v_exp_f32_e32 v46, v46
	v_exp_f32_e32 v48, v48
	v_exp_f32_e32 v51, v51
	v_add_f32_e32 v58, 1.0, v58
	v_add_f32_e32 v46, 1.0, v46
	v_add_f32_e32 v48, 1.0, v48
	v_rcp_f32_e32 v59, v46
	v_lshlrev_b32_e32 v46, 2, v132
	v_add_f32_e32 v51, 1.0, v51
	v_rcp_f32_e32 v78, v58
	v_rcp_f32_e32 v58, v48
	v_lshl_or_b32 v48, s14, 9, v46
	s_lshl_b64 s[14:15], s[54:55], 11
	v_rcp_f32_e32 v51, v51
	s_add_u32 s13, s13, s14
	v_readlane_b32 s14, v251, 46
	s_addc_u32 s14, s14, s15
	s_add_u32 s60, s13, s12
	v_div_scale_f32 v65, s[12:13], v53, v53, 1.0
	v_pk_mul_f32 v[50:51], v[50:51], v[66:67]
	v_rcp_f32_e32 v66, v65
	v_mul_f32_e32 v49, 0xbfb8aa3b, v49
	v_exp_f32_e32 v49, v49
	v_rcp_f32_e32 v94, v62
	v_fma_f32 v67, -v65, v66, 1.0
	v_fmac_f32_e32 v66, v67, v66
	v_div_scale_f32 v67, vcc, 1.0, v53, 1.0
	v_mul_f32_e32 v73, v67, v66
	v_fma_f32 v74, -v65, v73, v67
	v_fmac_f32_e32 v73, v74, v66
	v_fma_f32 v65, -v65, v73, v67
	v_div_fmas_f32 v65, v65, v66, v73
	v_div_fixup_f32 v109, v65, v53, 1.0
	v_div_scale_f32 v53, s[12:13], v52, v52, 1.0
	v_rcp_f32_e32 v65, v53
	v_add_f32_e32 v49, 1.0, v49
	v_rcp_f32_e32 v62, v49
	v_exp_f32_e32 v2, v2
	v_fma_f32 v66, -v53, v65, 1.0
	v_fmac_f32_e32 v65, v66, v65
	v_div_scale_f32 v66, vcc, 1.0, v52, 1.0
	v_mul_f32_e32 v67, v66, v65
	v_fma_f32 v73, -v53, v67, v66
	v_fmac_f32_e32 v67, v73, v65
	v_fma_f32 v53, -v53, v67, v66
	v_div_fmas_f32 v53, v53, v65, v67
	v_div_fixup_f32 v108, v53, v52, 1.0
	v_pk_add_f32 v[110:111], v[108:109], 1.0 op_sel_hi:[1,0] neg_lo:[1,0] neg_hi:[1,0]
	v_add_f32_e32 v2, 1.0, v2
	v_pk_fma_f32 v[52:53], v[110:111], v[54:55], v[108:109]
	v_pk_fma_f32 v[60:61], v[110:111], v[60:61], v[108:109]
	v_cmp_gt_f32_e32 vcc, s20, v52
	v_pk_fma_f32 v[68:69], v[110:111], v[68:69], v[108:109]
	v_pk_fma_f32 v[76:77], v[110:111], v[76:77], v[108:109]
	v_cndmask_b32_e64 v54, 0, 32, vcc
	v_ldexp_f32 v54, v52, v54
	v_log_f32_e32 v54, v54
	v_pk_fma_f32 v[84:85], v[110:111], v[84:85], v[108:109]
	v_pk_fma_f32 v[92:93], v[110:111], v[92:93], v[108:109]
	v_rcp_f32_e32 v5, v2
	v_mul_f32_e32 v55, 0x3f317217, v54
	v_fma_f32 v55, v54, s21, -v55
	v_fmac_f32_e32 v55, 0x3377d1cf, v54
	v_fmac_f32_e32 v55, 0x3f317217, v54
	v_cmp_lt_f32_e64 s[54:55], |v54|, s10
	v_pk_fma_f32 v[4:5], v[110:111], v[4:5], v[108:109]
	v_rcp_f32_e32 v7, v7
	v_cndmask_b32_e64 v54, v54, v55, s[54:55]
	v_cndmask_b32_e32 v55, 0, v223, vcc
	v_cmp_gt_f32_e32 vcc, s20, v53
	v_sub_f32_e32 v54, v54, v55
	s_waitcnt vmcnt(1)
	v_lshlrev_b32_e32 v2, 16, v0
	v_cndmask_b32_e64 v55, 0, 32, vcc
	v_ldexp_f32 v55, v53, v55
	v_log_f32_e32 v55, v55
	v_and_b32_e32 v0, 0xffff0000, v0
	v_mul_f32_e32 v2, 0xbfb8aa3b, v2
	v_mul_f32_e32 v0, 0xbfb8aa3b, v0
	v_mul_f32_e32 v65, 0x3f317217, v55
	v_fma_f32 v65, v55, s21, -v65
	v_fmac_f32_e32 v65, 0x3377d1cf, v55
	v_fmac_f32_e32 v65, 0x3f317217, v55
	v_cmp_lt_f32_e64 s[54:55], |v55|, s10
	v_exp_f32_e32 v2, v2
	v_exp_f32_e32 v0, v0
	v_cndmask_b32_e64 v55, v55, v65, s[54:55]
	v_cndmask_b32_e32 v65, 0, v223, vcc
	v_sub_f32_e32 v55, v55, v65
	v_div_scale_f32 v65, s[12:13], v57, v57, 1.0
	v_rcp_f32_e32 v66, v65
	v_pk_add_f32 v[54:55], v[54:55], 0 op_sel_hi:[1,0]
	v_add_f32_e32 v2, 1.0, v2
	v_add_f32_e32 v0, 1.0, v0
	v_fma_f32 v67, -v65, v66, 1.0
	v_fmac_f32_e32 v66, v67, v66
	v_div_scale_f32 v67, vcc, 1.0, v57, 1.0
	v_mul_f32_e32 v73, v67, v66
	v_fma_f32 v74, -v65, v73, v67
	v_fmac_f32_e32 v73, v74, v66
	v_fma_f32 v65, -v65, v73, v67
	v_div_fmas_f32 v65, v65, v66, v73
	v_div_fixup_f32 v113, v65, v57, 1.0
	v_div_scale_f32 v57, s[12:13], v56, v56, 1.0
	v_rcp_f32_e32 v65, v57
	v_rcp_f32_e32 v2, v2
	v_rcp_f32_e32 v3, v0
	s_waitcnt vmcnt(0)
	v_lshlrev_b32_e32 v0, 16, v1
	v_fma_f32 v66, -v57, v65, 1.0
	v_fmac_f32_e32 v65, v66, v65
	v_div_scale_f32 v66, vcc, 1.0, v56, 1.0
	v_mul_f32_e32 v67, v66, v65
	v_fma_f32 v73, -v57, v67, v66
	v_fmac_f32_e32 v67, v73, v65
	v_fma_f32 v57, -v57, v67, v66
	v_div_fmas_f32 v57, v57, v65, v67
	v_div_fixup_f32 v112, v57, v56, 1.0
	v_pk_add_f32 v[116:117], v[112:113], 1.0 op_sel_hi:[1,0] neg_lo:[1,0] neg_hi:[1,0]
	v_pk_fma_f32 v[2:3], v[110:111], v[2:3], v[108:109]
	v_pk_fma_f32 v[56:57], v[116:117], v[58:59], v[112:113]
	v_pk_fma_f32 v[62:63], v[116:117], v[62:63], v[112:113]
	v_cmp_gt_f32_e32 vcc, s20, v56
	v_pk_fma_f32 v[70:71], v[116:117], v[70:71], v[112:113]
	v_pk_fma_f32 v[78:79], v[116:117], v[78:79], v[112:113]
	v_cndmask_b32_e64 v58, 0, 32, vcc
	v_ldexp_f32 v58, v56, v58
	v_log_f32_e32 v58, v58
	v_pk_fma_f32 v[86:87], v[116:117], v[86:87], v[112:113]
	v_pk_fma_f32 v[94:95], v[116:117], v[94:95], v[112:113]
	v_pk_fma_f32 v[6:7], v[116:117], v[6:7], v[112:113]
	v_mul_f32_e32 v59, 0x3f317217, v58
	v_fma_f32 v59, v58, s21, -v59
	v_fmac_f32_e32 v59, 0x3377d1cf, v58
	v_fmac_f32_e32 v59, 0x3f317217, v58
	v_cmp_lt_f32_e64 s[54:55], |v58|, s10
	v_pk_add_f32 v[104:105], v[6:7], 1.0 op_sel_hi:[1,0] neg_lo:[1,0] neg_hi:[1,0]
	v_and_b32_e32 v1, 0xffff0000, v1
	v_cndmask_b32_e64 v58, v58, v59, s[54:55]
	v_cndmask_b32_e32 v59, 0, v223, vcc
	v_cmp_gt_f32_e32 vcc, s20, v57
	v_sub_f32_e32 v114, v58, v59
	v_mul_f32_e32 v0, 0xbfb8aa3b, v0
	v_cndmask_b32_e64 v58, 0, 32, vcc
	v_ldexp_f32 v58, v57, v58
	v_log_f32_e32 v58, v58
	v_mul_f32_e32 v1, 0xbfb8aa3b, v1
	v_exp_f32_e32 v0, v0
	v_exp_f32_e32 v1, v1
	v_mul_f32_e32 v59, 0x3f317217, v58
	v_fma_f32 v59, v58, s21, -v59
	v_fmac_f32_e32 v59, 0x3377d1cf, v58
	v_fmac_f32_e32 v59, 0x3f317217, v58
	v_cmp_lt_f32_e64 s[54:55], |v58|, s10
	v_add_f32_e32 v0, 1.0, v0
	v_add_f32_e32 v1, 1.0, v1
	v_cndmask_b32_e64 v58, v58, v59, s[54:55]
	v_cndmask_b32_e32 v59, 0, v223, vcc
	v_sub_f32_e32 v115, v58, v59
	v_pk_add_f32 v[58:59], v[56:57], 1.0 op_sel_hi:[1,0] neg_lo:[1,0] neg_hi:[1,0]
	v_lshlrev_b32_e32 v56, 16, v64
	v_and_b32_e32 v57, 0xffff0000, v64
	v_mul_f32_e32 v64, 0xbfb8aa3b, v56
	v_mul_f32_e32 v65, 0xbfb8aa3b, v57
	v_exp_f32_e32 v64, v64
	v_exp_f32_e32 v65, v65
	v_cmp_gt_f32_e32 vcc, s20, v60
	v_rcp_f32_e32 v0, v0
	v_add_f32_e32 v64, 1.0, v64
	v_add_f32_e32 v65, 1.0, v65
	v_rcp_f32_e32 v64, v64
	v_rcp_f32_e32 v65, v65
	v_rcp_f32_e32 v1, v1
	v_pk_add_f32 v[108:109], v[2:3], 1.0 op_sel_hi:[1,0] neg_lo:[1,0] neg_hi:[1,0]
	v_add_u32_e32 v141, 0, v48
	v_pk_mul_f32 v[56:57], v[64:65], v[56:57]
	v_cndmask_b32_e64 v64, 0, 32, vcc
	v_ldexp_f32 v64, v60, v64
	v_log_f32_e32 v64, v64
	v_pk_fma_f32 v[0:1], v[116:117], v[0:1], v[112:113]
	v_mov_b32_e32 v154, v55
	v_pk_add_f32 v[112:113], v[0:1], 1.0 op_sel_hi:[1,0] neg_lo:[1,0] neg_hi:[1,0]
	v_mul_f32_e32 v65, 0x3f317217, v64
	v_fma_f32 v65, v64, s21, -v65
	v_fmac_f32_e32 v65, 0x3377d1cf, v64
	v_fmac_f32_e32 v65, 0x3f317217, v64
	v_cmp_lt_f32_e64 s[54:55], |v64|, s10
	v_pk_mul_f32 v[50:51], v[50:51], s[6:7] op_sel_hi:[1,0]
	v_pk_add_f32 v[52:53], v[52:53], 1.0 op_sel_hi:[1,0] neg_lo:[1,0] neg_hi:[1,0]
	v_cndmask_b32_e64 v64, v64, v65, s[54:55]
	v_cndmask_b32_e32 v65, 0, v223, vcc
	v_cmp_gt_f32_e32 vcc, s20, v61
	v_sub_f32_e32 v64, v64, v65
	v_pk_mul_f32 v[56:57], v[56:57], s[6:7] op_sel_hi:[1,0]
	v_cndmask_b32_e64 v65, 0, 32, vcc
	v_ldexp_f32 v65, v61, v65
	v_log_f32_e32 v65, v65
	s_addc_u32 s61, s14, 0
	v_pk_add_f32 v[60:61], v[60:61], 1.0 op_sel_hi:[1,0] neg_lo:[1,0] neg_hi:[1,0]
	v_lshl_add_u64 v[48:49], s[60:61], 0, v[128:129]
	v_mul_f32_e32 v66, 0x3f317217, v65
	v_fma_f32 v66, v65, s21, -v66
	v_fmac_f32_e32 v66, 0x3377d1cf, v65
	v_fmac_f32_e32 v66, 0x3f317217, v65
	v_cmp_lt_f32_e64 s[54:55], |v65|, s10
	s_cmp_gt_u32 s9, 63
	s_nop 0
	v_cndmask_b32_e64 v65, v65, v66, s[54:55]
	v_cndmask_b32_e32 v66, 0, v223, vcc
	v_cmp_gt_f32_e32 vcc, s20, v62
	v_sub_f32_e32 v65, v65, v66
	v_pk_add_f32 v[64:65], v[54:55], v[64:65]
	v_cndmask_b32_e64 v66, 0, 32, vcc
	v_ldexp_f32 v66, v62, v66
	v_log_f32_e32 v66, v66
	s_nop 0
	v_mul_f32_e32 v67, 0x3f317217, v66
	v_fma_f32 v67, v66, s21, -v67
	v_fmac_f32_e32 v67, 0x3377d1cf, v66
	v_fmac_f32_e32 v67, 0x3f317217, v66
	v_cmp_lt_f32_e64 s[54:55], |v66|, s10
	s_nop 1
	v_cndmask_b32_e64 v66, v66, v67, s[54:55]
	v_cndmask_b32_e32 v67, 0, v223, vcc
	v_cmp_gt_f32_e32 vcc, s20, v63
	v_sub_f32_e32 v122, v66, v67
	s_nop 0
	v_cndmask_b32_e64 v66, 0, 32, vcc
	v_ldexp_f32 v66, v63, v66
	v_log_f32_e32 v66, v66
	s_nop 0
	v_mul_f32_e32 v67, 0x3f317217, v66
	v_fma_f32 v67, v66, s21, -v67
	v_fmac_f32_e32 v67, 0x3377d1cf, v66
	v_fmac_f32_e32 v67, 0x3f317217, v66
	v_cmp_lt_f32_e64 s[54:55], |v66|, s10
	s_nop 1
	v_cndmask_b32_e64 v66, v66, v67, s[54:55]
	v_cndmask_b32_e32 v67, 0, v223, vcc
	v_sub_f32_e32 v123, v66, v67
	v_pk_add_f32 v[66:67], v[62:63], 1.0 op_sel_hi:[1,0] neg_lo:[1,0] neg_hi:[1,0]
	v_lshlrev_b32_e32 v62, 16, v72
	v_and_b32_e32 v63, 0xffff0000, v72
	v_mul_f32_e32 v72, 0xbfb8aa3b, v62
	v_mul_f32_e32 v73, 0xbfb8aa3b, v63
	v_exp_f32_e32 v72, v72
	v_exp_f32_e32 v73, v73
	v_cmp_gt_f32_e32 vcc, s20, v68
	v_add_f32_e32 v72, 1.0, v72
	v_add_f32_e32 v73, 1.0, v73
	v_rcp_f32_e32 v72, v72
	v_rcp_f32_e32 v73, v73
	s_nop 0
	v_pk_mul_f32 v[62:63], v[72:73], v[62:63]
	v_cndmask_b32_e64 v72, 0, 32, vcc
	v_ldexp_f32 v72, v68, v72
	v_log_f32_e32 v72, v72
	v_pk_mul_f32 v[62:63], v[62:63], s[6:7] op_sel_hi:[1,0]
	v_mul_f32_e32 v73, 0x3f317217, v72
	v_fma_f32 v73, v72, s21, -v73
	v_fmac_f32_e32 v73, 0x3377d1cf, v72
	v_fmac_f32_e32 v73, 0x3f317217, v72
	v_cmp_lt_f32_e64 s[54:55], |v72|, s10
	s_nop 1
	v_cndmask_b32_e64 v72, v72, v73, s[54:55]
	v_cndmask_b32_e32 v73, 0, v223, vcc
	v_cmp_gt_f32_e32 vcc, s20, v69
	v_sub_f32_e32 v72, v72, v73
	s_nop 0
	v_cndmask_b32_e64 v73, 0, 32, vcc
	v_ldexp_f32 v73, v69, v73
	v_log_f32_e32 v73, v73
	v_pk_add_f32 v[68:69], v[68:69], 1.0 op_sel_hi:[1,0] neg_lo:[1,0] neg_hi:[1,0]
	v_mul_f32_e32 v74, 0x3f317217, v73
	v_fma_f32 v74, v73, s21, -v74
	v_fmac_f32_e32 v74, 0x3377d1cf, v73
	v_fmac_f32_e32 v74, 0x3f317217, v73
	v_cmp_lt_f32_e64 s[54:55], |v73|, s10
	s_nop 1
	v_cndmask_b32_e64 v73, v73, v74, s[54:55]
	v_cndmask_b32_e32 v74, 0, v223, vcc
	v_sub_f32_e32 v73, v73, v74
	v_cmp_gt_f32_e32 vcc, s20, v70
	v_pk_add_f32 v[74:75], v[64:65], v[72:73]
	s_nop 0
	v_cndmask_b32_e64 v72, 0, 32, vcc
	v_ldexp_f32 v72, v70, v72
	v_log_f32_e32 v72, v72
	s_nop 0
	v_mul_f32_e32 v73, 0x3f317217, v72
	v_fma_f32 v73, v72, s21, -v73
	v_fmac_f32_e32 v73, 0x3377d1cf, v72
	v_fmac_f32_e32 v73, 0x3f317217, v72
	v_cmp_lt_f32_e64 s[54:55], |v72|, s10
	s_nop 1
	v_cndmask_b32_e64 v72, v72, v73, s[54:55]
	v_cndmask_b32_e32 v73, 0, v223, vcc
	v_cmp_gt_f32_e32 vcc, s20, v71
	v_sub_f32_e32 v142, v72, v73
	s_nop 0
	v_cndmask_b32_e64 v72, 0, 32, vcc
	v_ldexp_f32 v72, v71, v72
	v_log_f32_e32 v72, v72
	s_nop 0
	v_mul_f32_e32 v73, 0x3f317217, v72
	v_fma_f32 v73, v72, s21, -v73
	v_fmac_f32_e32 v73, 0x3377d1cf, v72
	v_fmac_f32_e32 v73, 0x3f317217, v72
	v_cmp_lt_f32_e64 s[54:55], |v72|, s10
	s_nop 1
	v_cndmask_b32_e64 v72, v72, v73, s[54:55]
	v_cndmask_b32_e32 v73, 0, v223, vcc
	v_sub_f32_e32 v143, v72, v73
	v_pk_add_f32 v[72:73], v[70:71], 1.0 op_sel_hi:[1,0] neg_lo:[1,0] neg_hi:[1,0]
	v_lshlrev_b32_e32 v70, 16, v80
	v_and_b32_e32 v71, 0xffff0000, v80
	v_mul_f32_e32 v80, 0xbfb8aa3b, v70
	v_mul_f32_e32 v81, 0xbfb8aa3b, v71
	v_exp_f32_e32 v80, v80
	v_exp_f32_e32 v81, v81
	v_cmp_gt_f32_e32 vcc, s20, v76
	v_add_f32_e32 v80, 1.0, v80
	v_add_f32_e32 v81, 1.0, v81
	v_rcp_f32_e32 v80, v80
	v_rcp_f32_e32 v81, v81
	s_nop 0
	v_pk_mul_f32 v[70:71], v[80:81], v[70:71]
	v_cndmask_b32_e64 v80, 0, 32, vcc
	v_ldexp_f32 v80, v76, v80
	v_log_f32_e32 v80, v80
	v_pk_mul_f32 v[70:71], v[70:71], s[6:7] op_sel_hi:[1,0]
	v_mul_f32_e32 v81, 0x3f317217, v80
	v_fma_f32 v81, v80, s21, -v81
	v_fmac_f32_e32 v81, 0x3377d1cf, v80
	v_fmac_f32_e32 v81, 0x3f317217, v80
	v_cmp_lt_f32_e64 s[54:55], |v80|, s10
	s_nop 1
	v_cndmask_b32_e64 v80, v80, v81, s[54:55]
	v_cndmask_b32_e32 v81, 0, v223, vcc
	v_cmp_gt_f32_e32 vcc, s20, v77
	v_sub_f32_e32 v80, v80, v81
	s_nop 0
	v_cndmask_b32_e64 v81, 0, 32, vcc
	v_ldexp_f32 v81, v77, v81
	v_log_f32_e32 v81, v81
	v_pk_add_f32 v[76:77], v[76:77], 1.0 op_sel_hi:[1,0] neg_lo:[1,0] neg_hi:[1,0]
	v_mul_f32_e32 v82, 0x3f317217, v81
	v_fma_f32 v82, v81, s21, -v82
	v_fmac_f32_e32 v82, 0x3377d1cf, v81
	v_fmac_f32_e32 v82, 0x3f317217, v81
	v_cmp_lt_f32_e64 s[54:55], |v81|, s10
	s_nop 1
	v_cndmask_b32_e64 v81, v81, v82, s[54:55]
	v_cndmask_b32_e32 v82, 0, v223, vcc
	v_cmp_gt_f32_e32 vcc, s20, v78
	v_sub_f32_e32 v81, v81, v82
	v_pk_add_f32 v[80:81], v[74:75], v[80:81]
	v_cndmask_b32_e64 v82, 0, 32, vcc
	v_ldexp_f32 v82, v78, v82
	v_log_f32_e32 v82, v82
	s_nop 0
	v_mul_f32_e32 v83, 0x3f317217, v82
	v_fma_f32 v83, v82, s21, -v83
	v_fmac_f32_e32 v83, 0x3377d1cf, v82
	v_fmac_f32_e32 v83, 0x3f317217, v82
	v_cmp_lt_f32_e64 s[54:55], |v82|, s10
	s_nop 1
	v_cndmask_b32_e64 v82, v82, v83, s[54:55]
	v_cndmask_b32_e32 v83, 0, v223, vcc
	v_cmp_gt_f32_e32 vcc, s20, v79
	v_sub_f32_e32 v126, v82, v83
	s_nop 0
	v_cndmask_b32_e64 v82, 0, 32, vcc
	v_ldexp_f32 v82, v79, v82
	v_log_f32_e32 v82, v82
	s_nop 0
	v_mul_f32_e32 v83, 0x3f317217, v82
	v_fma_f32 v83, v82, s21, -v83
	v_fmac_f32_e32 v83, 0x3377d1cf, v82
	v_fmac_f32_e32 v83, 0x3f317217, v82
	v_cmp_lt_f32_e64 s[54:55], |v82|, s10
	s_nop 1
	v_cndmask_b32_e64 v82, v82, v83, s[54:55]
	v_cndmask_b32_e32 v83, 0, v223, vcc
	v_sub_f32_e32 v127, v82, v83
	v_pk_add_f32 v[82:83], v[78:79], 1.0 op_sel_hi:[1,0] neg_lo:[1,0] neg_hi:[1,0]
	v_lshlrev_b32_e32 v78, 16, v88
	v_and_b32_e32 v79, 0xffff0000, v88
	v_mul_f32_e32 v88, 0xbfb8aa3b, v78
	v_mul_f32_e32 v89, 0xbfb8aa3b, v79
	v_exp_f32_e32 v88, v88
	v_exp_f32_e32 v89, v89
	v_cmp_gt_f32_e32 vcc, s20, v84
	v_add_f32_e32 v88, 1.0, v88
	v_add_f32_e32 v89, 1.0, v89
	v_rcp_f32_e32 v88, v88
	v_rcp_f32_e32 v89, v89
	s_nop 0
	v_pk_mul_f32 v[78:79], v[88:89], v[78:79]
	v_cndmask_b32_e64 v88, 0, 32, vcc
	v_ldexp_f32 v88, v84, v88
	v_log_f32_e32 v88, v88
	v_pk_mul_f32 v[78:79], v[78:79], s[6:7] op_sel_hi:[1,0]
	v_mul_f32_e32 v89, 0x3f317217, v88
	v_fma_f32 v89, v88, s21, -v89
	v_fmac_f32_e32 v89, 0x3377d1cf, v88
	v_fmac_f32_e32 v89, 0x3f317217, v88
	v_cmp_lt_f32_e64 s[54:55], |v88|, s10
	s_nop 1
	v_cndmask_b32_e64 v88, v88, v89, s[54:55]
	v_cndmask_b32_e32 v89, 0, v223, vcc
	v_cmp_gt_f32_e32 vcc, s20, v85
	v_sub_f32_e32 v88, v88, v89
	s_nop 0
	v_cndmask_b32_e64 v89, 0, 32, vcc
	v_ldexp_f32 v89, v85, v89
	v_log_f32_e32 v89, v89
	v_pk_add_f32 v[84:85], v[84:85], 1.0 op_sel_hi:[1,0] neg_lo:[1,0] neg_hi:[1,0]
	v_mul_f32_e32 v90, 0x3f317217, v89
	v_fma_f32 v90, v89, s21, -v90
	v_fmac_f32_e32 v90, 0x3377d1cf, v89
	v_fmac_f32_e32 v90, 0x3f317217, v89
	v_cmp_lt_f32_e64 s[54:55], |v89|, s10
	s_nop 1
	v_cndmask_b32_e64 v89, v89, v90, s[54:55]
	v_cndmask_b32_e32 v90, 0, v223, vcc
	v_cmp_gt_f32_e32 vcc, s20, v86
	v_sub_f32_e32 v89, v89, v90
	v_pk_add_f32 v[88:89], v[80:81], v[88:89]
	v_cndmask_b32_e64 v90, 0, 32, vcc
	v_ldexp_f32 v90, v86, v90
	v_log_f32_e32 v90, v90
	s_nop 0
	v_mul_f32_e32 v91, 0x3f317217, v90
	v_fma_f32 v91, v90, s21, -v91
	v_fmac_f32_e32 v91, 0x3377d1cf, v90
	v_fmac_f32_e32 v91, 0x3f317217, v90
	v_cmp_lt_f32_e64 s[54:55], |v90|, s10
	s_nop 1
	v_cndmask_b32_e64 v90, v90, v91, s[54:55]
	v_cndmask_b32_e32 v91, 0, v223, vcc
	v_cmp_gt_f32_e32 vcc, s20, v87
	v_sub_f32_e32 v124, v90, v91
	s_nop 0
	v_cndmask_b32_e64 v90, 0, 32, vcc
	v_ldexp_f32 v90, v87, v90
	v_log_f32_e32 v90, v90
	s_nop 0
	v_mul_f32_e32 v91, 0x3f317217, v90
	v_fma_f32 v91, v90, s21, -v91
	v_fmac_f32_e32 v91, 0x3377d1cf, v90
	v_fmac_f32_e32 v91, 0x3f317217, v90
	v_cmp_lt_f32_e64 s[54:55], |v90|, s10
	s_nop 1
	v_cndmask_b32_e64 v90, v90, v91, s[54:55]
	v_cndmask_b32_e32 v91, 0, v223, vcc
	v_sub_f32_e32 v125, v90, v91
	v_pk_add_f32 v[90:91], v[86:87], 1.0 op_sel_hi:[1,0] neg_lo:[1,0] neg_hi:[1,0]
	v_lshlrev_b32_e32 v86, 16, v96
	v_and_b32_e32 v87, 0xffff0000, v96
	v_mul_f32_e32 v96, 0xbfb8aa3b, v86
	v_mul_f32_e32 v97, 0xbfb8aa3b, v87
	v_exp_f32_e32 v96, v96
	v_exp_f32_e32 v97, v97
	v_cmp_gt_f32_e32 vcc, s20, v92
	v_add_f32_e32 v96, 1.0, v96
	v_add_f32_e32 v97, 1.0, v97
	v_rcp_f32_e32 v96, v96
	v_rcp_f32_e32 v97, v97
	s_nop 0
	v_pk_mul_f32 v[86:87], v[96:97], v[86:87]
	v_cndmask_b32_e64 v96, 0, 32, vcc
	v_ldexp_f32 v96, v92, v96
	v_log_f32_e32 v96, v96
	v_pk_mul_f32 v[86:87], v[86:87], s[6:7] op_sel_hi:[1,0]
	v_mul_f32_e32 v97, 0x3f317217, v96
	v_fma_f32 v97, v96, s21, -v97
	v_fmac_f32_e32 v97, 0x3377d1cf, v96
	v_fmac_f32_e32 v97, 0x3f317217, v96
	v_cmp_lt_f32_e64 s[54:55], |v96|, s10
	s_nop 1
	v_cndmask_b32_e64 v96, v96, v97, s[54:55]
	v_cndmask_b32_e32 v97, 0, v223, vcc
	v_cmp_gt_f32_e32 vcc, s20, v93
	v_sub_f32_e32 v96, v96, v97
	s_nop 0
	v_cndmask_b32_e64 v97, 0, 32, vcc
	v_ldexp_f32 v97, v93, v97
	v_log_f32_e32 v97, v97
	v_pk_add_f32 v[92:93], v[92:93], 1.0 op_sel_hi:[1,0] neg_lo:[1,0] neg_hi:[1,0]
	v_mul_f32_e32 v98, 0x3f317217, v97
	v_fma_f32 v98, v97, s21, -v98
	v_fmac_f32_e32 v98, 0x3377d1cf, v97
	v_fmac_f32_e32 v98, 0x3f317217, v97
	v_cmp_lt_f32_e64 s[54:55], |v97|, s10
	s_nop 1
	v_cndmask_b32_e64 v97, v97, v98, s[54:55]
	v_cndmask_b32_e32 v98, 0, v223, vcc
	v_cmp_gt_f32_e32 vcc, s20, v94
	v_sub_f32_e32 v97, v97, v98
	v_pk_add_f32 v[96:97], v[88:89], v[96:97]
	v_cndmask_b32_e64 v98, 0, 32, vcc
	v_ldexp_f32 v98, v94, v98
	v_log_f32_e32 v98, v98
	s_nop 0
	v_mul_f32_e32 v99, 0x3f317217, v98
	v_fma_f32 v99, v98, s21, -v99
	v_fmac_f32_e32 v99, 0x3377d1cf, v98
	v_fmac_f32_e32 v99, 0x3f317217, v98
	v_cmp_lt_f32_e64 s[54:55], |v98|, s10
	s_nop 1
	v_cndmask_b32_e64 v98, v98, v99, s[54:55]
	v_cndmask_b32_e32 v99, 0, v223, vcc
	v_cmp_gt_f32_e32 vcc, s20, v95
	v_sub_f32_e32 v120, v98, v99
	s_nop 0
	v_cndmask_b32_e64 v98, 0, 32, vcc
	v_ldexp_f32 v98, v95, v98
	v_log_f32_e32 v98, v98
	s_nop 0
	v_mul_f32_e32 v99, 0x3f317217, v98
	v_fma_f32 v99, v98, s21, -v99
	v_fmac_f32_e32 v99, 0x3377d1cf, v98
	v_fmac_f32_e32 v99, 0x3f317217, v98
	v_cmp_lt_f32_e64 s[54:55], |v98|, s10
	s_nop 1
	v_cndmask_b32_e64 v98, v98, v99, s[54:55]
	v_cndmask_b32_e32 v99, 0, v223, vcc
	v_sub_f32_e32 v121, v98, v99
	v_pk_add_f32 v[98:99], v[94:95], 1.0 op_sel_hi:[1,0] neg_lo:[1,0] neg_hi:[1,0]
	v_lshlrev_b32_e32 v94, 16, v100
	v_and_b32_e32 v95, 0xffff0000, v100
	v_mul_f32_e32 v100, 0xbfb8aa3b, v94
	v_mul_f32_e32 v101, 0xbfb8aa3b, v95
	v_exp_f32_e32 v100, v100
	v_exp_f32_e32 v101, v101
	v_cmp_gt_f32_e32 vcc, s20, v4
	v_add_f32_e32 v100, 1.0, v100
	v_add_f32_e32 v101, 1.0, v101
	v_rcp_f32_e32 v100, v100
	v_rcp_f32_e32 v101, v101
	s_nop 0
	v_pk_mul_f32 v[94:95], v[100:101], v[94:95]
	v_cndmask_b32_e64 v100, 0, 32, vcc
	v_ldexp_f32 v100, v4, v100
	v_log_f32_e32 v100, v100
	v_pk_mul_f32 v[94:95], v[94:95], s[6:7] op_sel_hi:[1,0]
	v_mul_f32_e32 v101, 0x3f317217, v100
	v_fma_f32 v101, v100, s21, -v101
	v_fmac_f32_e32 v101, 0x3377d1cf, v100
	v_fmac_f32_e32 v101, 0x3f317217, v100
	v_cmp_lt_f32_e64 s[54:55], |v100|, s10
	s_nop 1
	v_cndmask_b32_e64 v100, v100, v101, s[54:55]
	v_cndmask_b32_e32 v101, 0, v223, vcc
	v_cmp_gt_f32_e32 vcc, s20, v5
	v_sub_f32_e32 v102, v100, v101
	s_nop 0
	v_cndmask_b32_e64 v100, 0, 32, vcc
	v_ldexp_f32 v100, v5, v100
	v_log_f32_e32 v100, v100
	s_nop 0
	v_mul_f32_e32 v101, 0x3f317217, v100
	v_fma_f32 v101, v100, s21, -v101
	v_fmac_f32_e32 v101, 0x3377d1cf, v100
	v_fmac_f32_e32 v101, 0x3f317217, v100
	v_cmp_lt_f32_e64 s[54:55], |v100|, s10
	s_nop 1
	v_cndmask_b32_e64 v100, v100, v101, s[54:55]
	v_cndmask_b32_e32 v101, 0, v223, vcc
	v_cmp_gt_f32_e32 vcc, s20, v6
	v_sub_f32_e32 v103, v100, v101
	v_pk_add_f32 v[100:101], v[4:5], 1.0 op_sel_hi:[1,0] neg_lo:[1,0] neg_hi:[1,0]
	v_cndmask_b32_e64 v4, 0, 32, vcc
	v_ldexp_f32 v4, v6, v4
	v_log_f32_e32 v4, v4
	v_lshlrev_b32_e32 v6, 16, v47
	v_pk_add_f32 v[106:107], v[96:97], v[102:103]
	v_mul_f32_e32 v5, 0x3f317217, v4
	v_fma_f32 v5, v4, s21, -v5
	v_fmac_f32_e32 v5, 0x3377d1cf, v4
	v_fmac_f32_e32 v5, 0x3f317217, v4
	v_cmp_lt_f32_e64 s[54:55], |v4|, s10
	s_nop 1
	v_cndmask_b32_e64 v4, v4, v5, s[54:55]
	v_cndmask_b32_e32 v5, 0, v223, vcc
	v_cmp_gt_f32_e32 vcc, s20, v7
	v_sub_f32_e32 v4, v4, v5
	s_nop 0
	v_cndmask_b32_e64 v5, 0, 32, vcc
	v_ldexp_f32 v5, v7, v5
	v_log_f32_e32 v5, v5
	v_and_b32_e32 v7, 0xffff0000, v47
	v_mul_f32_e32 v47, 0xbfb8aa3b, v6
	v_exp_f32_e32 v47, v47
	v_mul_f32_e32 v102, 0x3f317217, v5
	v_fma_f32 v102, v5, s21, -v102
	v_fmac_f32_e32 v102, 0x3377d1cf, v5
	v_fmac_f32_e32 v102, 0x3f317217, v5
	v_cmp_lt_f32_e64 s[54:55], |v5|, s10
	v_add_f32_e32 v47, 1.0, v47
	s_nop 0
	v_cndmask_b32_e64 v5, v5, v102, s[54:55]
	v_cndmask_b32_e32 v102, 0, v223, vcc
	v_sub_f32_e32 v5, v5, v102
	v_rcp_f32_e32 v102, v47
	v_mul_f32_e32 v47, 0xbfb8aa3b, v7
	v_exp_f32_e32 v47, v47
	v_cmp_gt_f32_e32 vcc, s20, v2
	v_add_f32_e32 v47, 1.0, v47
	v_rcp_f32_e32 v103, v47
	s_nop 0
	v_pk_mul_f32 v[6:7], v[102:103], v[6:7]
	s_nop 0
	v_pk_mul_f32 v[102:103], v[6:7], s[6:7] op_sel_hi:[1,0]
	v_cndmask_b32_e64 v6, 0, 32, vcc
	v_ldexp_f32 v6, v2, v6
	v_log_f32_e32 v6, v6
	s_nop 0
	v_mul_f32_e32 v7, 0x3f317217, v6
	v_fma_f32 v7, v6, s21, -v7
	v_fmac_f32_e32 v7, 0x3377d1cf, v6
	v_fmac_f32_e32 v7, 0x3f317217, v6
	v_cmp_lt_f32_e64 s[54:55], |v6|, s10
	s_nop 1
	v_cndmask_b32_e64 v6, v6, v7, s[54:55]
	v_cndmask_b32_e32 v7, 0, v223, vcc
	v_cmp_gt_f32_e32 vcc, s20, v3
	v_sub_f32_e32 v6, v6, v7
	s_nop 0
	v_cndmask_b32_e64 v7, 0, 32, vcc
	v_ldexp_f32 v7, v3, v7
	v_log_f32_e32 v7, v7
	s_nop 0
	v_mul_f32_e32 v47, 0x3f317217, v7
	v_fma_f32 v47, v7, s21, -v47
	v_fmac_f32_e32 v47, 0x3377d1cf, v7
	v_fmac_f32_e32 v47, 0x3f317217, v7
	v_cmp_lt_f32_e64 s[54:55], |v7|, s10
	s_nop 1
	v_cndmask_b32_e64 v7, v7, v47, s[54:55]
	v_cndmask_b32_e32 v47, 0, v223, vcc
	v_cmp_gt_f32_e32 vcc, s20, v0
	v_sub_f32_e32 v7, v7, v47
	v_pk_add_f32 v[110:111], v[106:107], v[6:7]
	v_cndmask_b32_e64 v2, 0, 32, vcc
	v_ldexp_f32 v2, v0, v2
	v_log_f32_e32 v2, v2
	s_nop 0
	v_mul_f32_e32 v3, 0x3f317217, v2
	v_fma_f32 v3, v2, s21, -v3
	v_fmac_f32_e32 v3, 0x3377d1cf, v2
	v_fmac_f32_e32 v3, 0x3f317217, v2
	v_cmp_lt_f32_e64 s[54:55], |v2|, s10
	s_nop 1
	v_cndmask_b32_e64 v2, v2, v3, s[54:55]
	v_cndmask_b32_e32 v3, 0, v223, vcc
	v_cmp_gt_f32_e32 vcc, s20, v1
	v_sub_f32_e32 v2, v2, v3
	s_nop 0
	v_cndmask_b32_e64 v3, 0, 32, vcc
	v_ldexp_f32 v3, v1, v3
	v_log_f32_e32 v3, v3
	s_nop 0
	v_mul_f32_e32 v6, 0x3f317217, v3
	v_fma_f32 v6, v3, s21, -v6
	v_fmac_f32_e32 v6, 0x3377d1cf, v3
	v_fmac_f32_e32 v6, 0x3f317217, v3
	v_cmp_lt_f32_e64 s[54:55], |v3|, s10
	s_nop 1
	v_cndmask_b32_e64 v3, v3, v6, s[54:55]
	v_cndmask_b32_e32 v6, 0, v223, vcc
	v_sub_f32_e32 v3, v3, v6
	v_pk_add_f32 v[116:117], v[2:3], 0 op_sel_hi:[1,0]
	s_nop 0
	v_pk_add_f32 v[118:119], v[4:5], v[116:117]
	s_nop 0
	v_pk_add_f32 v[120:121], v[120:121], v[118:119]
	s_nop 0
	v_pk_add_f32 v[124:125], v[124:125], v[120:121]
	s_nop 0
	v_pk_add_f32 v[126:127], v[126:127], v[124:125]
	s_nop 0
	v_pk_add_f32 v[142:143], v[142:143], v[126:127]
	s_nop 0
	v_pk_add_f32 v[122:123], v[122:123], v[142:143]
	s_nop 0
	v_pk_add_f32 v[114:115], v[114:115], v[122:123]
	ds_write2st64_b64 v141, v[110:111], v[114:115] offset1:8
	s_waitcnt lgkmcnt(0)
	s_barrier
	ds_read2st64_b64 v[0:3], v207 offset1:1
	ds_read2st64_b64 v[4:7], v207 offset0:8 offset1:9
	v_mov_b32_e32 v152, v114
	s_waitcnt lgkmcnt(1)
	v_add_f32_e32 v0, 0, v0
	v_add_f32_e32 v1, 0, v1
	v_cndmask_b32_e64 v47, v1, 0, s[50:51]
	v_cndmask_b32_e64 v141, v0, 0, s[50:51]
	v_add_f32_e32 v144, v0, v2
	v_add_f32_e32 v145, v1, v3
	v_add_f32_e32 v0, v141, v2
	v_add_f32_e32 v1, v47, v3
	s_waitcnt lgkmcnt(0)
	v_add_f32_e32 v4, 0, v4
	v_add_f32_e32 v5, 0, v5
	v_cndmask_b32_e64 v47, v47, v1, s[52:53]
	v_cndmask_b32_e64 v141, v141, v0, s[52:53]
	v_add_f32_e32 v0, 0, v6
	v_add_f32_e32 v1, 0, v7
	v_add_f32_e32 v146, v4, v6
	v_add_f32_e32 v147, v5, v7
	v_cndmask_b32_e64 v148, 0, v1, s[50:51]
	v_cndmask_b32_e64 v149, 0, v0, s[50:51]
	ds_read2st64_b64 v[0:3], v207 offset0:2 offset1:3
	ds_read2st64_b64 v[4:7], v207 offset0:10 offset1:11
	s_waitcnt lgkmcnt(1)
	v_add_f32_e32 v144, v144, v0
	v_add_f32_e32 v145, v145, v1
	v_add_f32_e32 v0, v141, v0
	v_add_f32_e32 v1, v47, v1
	s_waitcnt lgkmcnt(0)
	v_add_f32_e32 v146, v146, v4
	v_add_f32_e32 v147, v147, v5
	v_cndmask_b32_e64 v1, v47, v1, s[48:49]
	v_cndmask_b32_e64 v0, v141, v0, s[48:49]
	v_add_f32_e32 v4, v149, v4
	v_add_f32_e32 v5, v148, v5
	v_cndmask_b32_e64 v5, 0, v5, s[46:47]
	v_cndmask_b32_e64 v4, 0, v4, s[46:47]
	v_add_f32_e32 v47, v144, v2
	v_add_f32_e32 v141, v145, v3
	v_add_f32_e32 v2, v0, v2
	v_add_f32_e32 v3, v1, v3
	v_add_f32_e32 v144, v146, v6
	v_add_f32_e32 v145, v147, v7
	v_cndmask_b32_e64 v146, v1, v3, s[44:45]
	v_cndmask_b32_e64 v147, v0, v2, s[44:45]
	v_add_f32_e32 v0, v4, v6
	v_add_f32_e32 v1, v5, v7
	v_cndmask_b32_e64 v148, 0, v1, s[42:43]
	v_cndmask_b32_e64 v149, 0, v0, s[42:43]
	ds_read2st64_b64 v[0:3], v207 offset0:4 offset1:5
	ds_read2st64_b64 v[4:7], v207 offset0:12 offset1:13
	s_waitcnt lgkmcnt(1)
	v_add_f32_e32 v47, v47, v0
	v_add_f32_e32 v141, v141, v1
	v_add_f32_e32 v0, v147, v0
	v_add_f32_e32 v1, v146, v1
	s_waitcnt lgkmcnt(0)
	v_add_f32_e32 v144, v144, v4
	v_add_f32_e32 v145, v145, v5
	v_cndmask_b32_e64 v1, v146, v1, s[40:41]
	v_cndmask_b32_e64 v0, v147, v0, s[40:41]
	v_add_f32_e32 v4, v149, v4
	v_add_f32_e32 v5, v148, v5
	v_cndmask_b32_e64 v5, 0, v5, s[38:39]
	v_cndmask_b32_e64 v4, 0, v4, s[38:39]
	v_add_f32_e32 v47, v47, v2
	v_add_f32_e32 v141, v141, v3
	v_add_f32_e32 v2, v0, v2
	v_add_f32_e32 v3, v1, v3
	v_cndmask_b32_e64 v147, v1, v3, s[36:37]
	v_cndmask_b32_e64 v148, v0, v2, s[36:37]
	v_add_f32_e32 v0, v4, v6
	v_add_f32_e32 v1, v5, v7
	v_add_f32_e32 v144, v144, v6
	v_add_f32_e32 v146, v145, v7
	v_cndmask_b32_e64 v149, 0, v1, s[34:35]
	v_cndmask_b32_e64 v150, 0, v0, s[34:35]
	ds_read2st64_b64 v[0:3], v207 offset0:6 offset1:7
	ds_read2st64_b64 v[4:7], v207 offset0:14 offset1:15
	s_waitcnt lgkmcnt(1)
	v_add_f32_e32 v145, v47, v0
	v_add_f32_e32 v0, v148, v0
	s_waitcnt lgkmcnt(0)
	v_add_f32_e32 v153, v144, v4
	v_cndmask_b32_e64 v47, v148, v0, s[30:31]
	v_add_f32_e32 v0, v150, v4
	v_add_f32_e32 v4, v149, v5
	v_add_f32_e32 v155, v141, v1
	v_add_f32_e32 v151, v146, v5
	v_add_f32_e32 v1, v147, v1
	v_cndmask_b32_e64 v5, 0, v4, s[28:29]
	v_cndmask_b32_e64 v1, v147, v1, s[30:31]
	v_add_f32_e32 v4, v47, v2
	v_add_f32_e32 v5, v5, v7
	v_cndmask_b32_e64 v141, 0, v0, s[28:29]
	v_add_f32_e32 v0, v1, v3
	v_cndmask_b32_e64 v4, v47, v4, s[26:27]
	v_cndmask_b32_e64 v146, 0, v5, s[24:25]
	v_mov_b32_e32 v144, v54
	v_mov_b32_e32 v5, v2
	v_cndmask_b32_e64 v0, v1, v0, s[26:27]
	v_add_f32_e32 v1, v141, v6
	v_pk_add_f32 v[144:145], v[144:145], v[4:5]
	v_cndmask_b32_e64 v148, 0, v1, s[24:25]
	v_sub_f32_e32 v5, v144, v145
	v_mov_b32_e32 v1, v3
	v_pk_add_f32 v[54:55], v[154:155], v[0:1]
	v_min_f32_e32 v47, 0x42a00000, v5
	v_sub_f32_e32 v1, v54, v55
	v_mul_f32_e32 v47, 0x3fb8aa3b, v47
	v_exp_f32_e32 v114, v47
	v_min_f32_e32 v47, 0x42a00000, v1
	v_mul_f32_e32 v47, 0x3fb8aa3b, v47
	v_mov_b32_e32 v150, v115
	v_exp_f32_e32 v115, v47
	v_mov_b32_e32 v149, v6
	v_pk_add_f32 v[2:3], v[152:153], v[148:149]
	v_mov_b32_e32 v147, v7
	v_pk_mul_f32 v[114:115], v[50:51], v[114:115]
	v_sub_f32_e32 v2, v2, v3
	v_cvt_pk_bf16_f32 v47, v114, v115
	v_pk_add_f32 v[6:7], v[150:151], v[146:147]
	global_store_dword v128, v47, s[58:59]
	v_min_f32_e32 v47, 0x42a00000, v2
	v_sub_f32_e32 v6, v6, v7
	v_mul_f32_e32 v47, 0x3fb8aa3b, v47
	v_exp_f32_e32 v114, v47
	v_min_f32_e32 v47, 0x42a00000, v6
	v_mul_f32_e32 v47, 0x3fb8aa3b, v47
	v_exp_f32_e32 v115, v47
	v_mul_f32_e32 v5, 0xbfb8aa3b, v5
	v_mul_f32_e32 v1, 0xbfb8aa3b, v1
	v_pk_mul_f32 v[50:51], v[50:51], v[114:115]
	s_nop 0
	v_cvt_pk_bf16_f32 v47, v50, v51
	v_exp_f32_e32 v50, v5
	v_exp_f32_e32 v51, v1
	v_add_f32_e32 v5, v122, v148
	v_sub_f32_e32 v5, v5, v3
	global_store_dword v128, v47, s[60:61]
	v_pk_mul_f32 v[50:51], v[52:53], v[50:51]
	s_nop 0
	v_cvt_pk_bf16_f32 v1, v50, v51
	global_store_dword v[44:45], v1, off offset:2048
	v_mul_f32_e32 v1, 0xbfb8aa3b, v2
	v_exp_f32_e32 v44, v1
	v_mul_f32_e32 v1, 0xbfb8aa3b, v6
	v_exp_f32_e32 v45, v1
	v_add_f32_e32 v2, v65, v0
	v_sub_f32_e32 v2, v2, v55
	v_add_f32_e32 v6, v123, v146
	v_pk_mul_f32 v[44:45], v[58:59], v[44:45]
	v_sub_f32_e32 v6, v6, v7
	v_cvt_pk_bf16_f32 v1, v44, v45
	global_store_dword v[42:43], v1, off
	v_add_f32_e32 v1, v64, v4
	v_sub_f32_e32 v1, v1, v145
	v_min_f32_e32 v42, 0x42a00000, v1
	v_min_f32_e32 v43, 0x42a00000, v2
	v_mul_f32_e32 v42, 0x3fb8aa3b, v42
	v_mul_f32_e32 v43, 0x3fb8aa3b, v43
	v_exp_f32_e32 v42, v42
	v_exp_f32_e32 v43, v43
	v_mul_f32_e32 v1, 0xbfb8aa3b, v1
	v_pk_mul_f32 v[42:43], v[56:57], v[42:43]
	s_nop 0
	v_cvt_pk_bf16_f32 v42, v42, v43
	global_store_dword v[40:41], v42, off offset:2048
	v_min_f32_e32 v40, 0x42a00000, v5
	v_min_f32_e32 v41, 0x42a00000, v6
	v_mul_f32_e32 v40, 0x3fb8aa3b, v40
	v_mul_f32_e32 v41, 0x3fb8aa3b, v41
	v_exp_f32_e32 v40, v40
	v_exp_f32_e32 v41, v41
	s_nop 0
	v_pk_mul_f32 v[40:41], v[56:57], v[40:41]
	s_nop 0
	v_cvt_pk_bf16_f32 v40, v40, v41
	global_store_dword v128, v40, s[60:61] offset:2048
	v_exp_f32_e32 v40, v1
	v_mul_f32_e32 v1, 0xbfb8aa3b, v2
	v_exp_f32_e32 v41, v1
	v_add_f32_e32 v2, v75, v0
	v_sub_f32_e32 v2, v2, v55
	v_pk_mul_f32 v[40:41], v[60:61], v[40:41]
	s_nop 0
	v_cvt_pk_bf16_f32 v1, v40, v41
	global_store_dword v[38:39], v1, off
	v_mul_f32_e32 v1, 0xbfb8aa3b, v5
	v_exp_f32_e32 v40, v1
	v_mul_f32_e32 v1, 0xbfb8aa3b, v6
	v_exp_f32_e32 v41, v1
	v_add_f32_e32 v5, v142, v148
	v_add_f32_e32 v6, v143, v146
	v_sub_f32_e32 v5, v5, v3
	v_pk_mul_f32 v[40:41], v[66:67], v[40:41]
	v_sub_f32_e32 v6, v6, v7
	v_cvt_pk_bf16_f32 v1, v40, v41
	global_store_dword v[38:39], v1, off offset:2048
	v_add_f32_e32 v1, v74, v4
	v_sub_f32_e32 v1, v1, v145
	v_min_f32_e32 v38, 0x42a00000, v1
	v_min_f32_e32 v39, 0x42a00000, v2
	v_mul_f32_e32 v38, 0x3fb8aa3b, v38
	v_mul_f32_e32 v39, 0x3fb8aa3b, v39
	v_exp_f32_e32 v38, v38
	v_exp_f32_e32 v39, v39
	v_mul_f32_e32 v1, 0xbfb8aa3b, v1
	v_pk_mul_f32 v[38:39], v[62:63], v[38:39]
	s_nop 0
	v_cvt_pk_bf16_f32 v38, v38, v39
	global_store_dword v[36:37], v38, off
	v_min_f32_e32 v36, 0x42a00000, v5
	v_min_f32_e32 v37, 0x42a00000, v6
	v_mul_f32_e32 v36, 0x3fb8aa3b, v36
	v_mul_f32_e32 v37, 0x3fb8aa3b, v37
	v_exp_f32_e32 v36, v36
	v_exp_f32_e32 v37, v37
	v_add_co_u32_e32 v38, vcc, s7, v48
	v_pk_mul_f32 v[36:37], v[62:63], v[36:37]
	s_nop 0
	v_addc_co_u32_e32 v39, vcc, 0, v49, vcc
	v_cvt_pk_bf16_f32 v40, v36, v37
	v_add_co_u32_e32 v36, vcc, s62, v48
	s_nop 1
	v_addc_co_u32_e32 v37, vcc, 0, v49, vcc
	global_store_dword v[36:37], v40, off offset:-4096
	v_exp_f32_e32 v40, v1
	v_mul_f32_e32 v1, 0xbfb8aa3b, v2
	v_exp_f32_e32 v41, v1
	v_add_f32_e32 v2, v81, v0
	v_sub_f32_e32 v2, v2, v55
	v_pk_mul_f32 v[40:41], v[68:69], v[40:41]
	s_nop 0
	v_cvt_pk_bf16_f32 v1, v40, v41
	global_store_dword v[34:35], v1, off offset:2048
	v_mul_f32_e32 v1, 0xbfb8aa3b, v5
	v_exp_f32_e32 v34, v1
	v_mul_f32_e32 v1, 0xbfb8aa3b, v6
	v_exp_f32_e32 v35, v1
	v_add_f32_e32 v5, v126, v148
	v_add_f32_e32 v6, v127, v146
	v_sub_f32_e32 v5, v5, v3
	v_pk_mul_f32 v[34:35], v[72:73], v[34:35]
	v_sub_f32_e32 v6, v6, v7
	v_cvt_pk_bf16_f32 v1, v34, v35
	global_store_dword v[30:31], v1, off
	v_add_f32_e32 v1, v80, v4
	v_sub_f32_e32 v1, v1, v145
	v_min_f32_e32 v30, 0x42a00000, v1
	v_min_f32_e32 v31, 0x42a00000, v2
	v_mul_f32_e32 v30, 0x3fb8aa3b, v30
	v_mul_f32_e32 v31, 0x3fb8aa3b, v31
	v_exp_f32_e32 v30, v30
	v_exp_f32_e32 v31, v31
	v_mul_f32_e32 v1, 0xbfb8aa3b, v1
	v_pk_mul_f32 v[30:31], v[70:71], v[30:31]
	s_nop 0
	v_cvt_pk_bf16_f32 v30, v30, v31
	global_store_dword v[32:33], v30, off offset:2048
	v_min_f32_e32 v30, 0x42a00000, v5
	v_min_f32_e32 v31, 0x42a00000, v6
	v_mul_f32_e32 v30, 0x3fb8aa3b, v30
	v_mul_f32_e32 v31, 0x3fb8aa3b, v31
	v_exp_f32_e32 v30, v30
	v_exp_f32_e32 v31, v31
	s_nop 0
	v_pk_mul_f32 v[30:31], v[70:71], v[30:31]
	s_nop 0
	v_cvt_pk_bf16_f32 v30, v30, v31
	global_store_dword v[38:39], v30, off offset:2048
	v_exp_f32_e32 v30, v1
	v_mul_f32_e32 v1, 0xbfb8aa3b, v2
	v_exp_f32_e32 v31, v1
	v_add_f32_e32 v2, v89, v0
	v_sub_f32_e32 v2, v2, v55
	v_pk_mul_f32 v[30:31], v[76:77], v[30:31]
	s_nop 0
	v_cvt_pk_bf16_f32 v1, v30, v31
	global_store_dword v[28:29], v1, off
	v_mul_f32_e32 v1, 0xbfb8aa3b, v5
	v_exp_f32_e32 v30, v1
	v_mul_f32_e32 v1, 0xbfb8aa3b, v6
	v_exp_f32_e32 v31, v1
	v_add_f32_e32 v5, v124, v148
	v_add_f32_e32 v6, v125, v146
	v_sub_f32_e32 v5, v5, v3
	v_pk_mul_f32 v[30:31], v[82:83], v[30:31]
	v_sub_f32_e32 v6, v6, v7
	v_cvt_pk_bf16_f32 v1, v30, v31
	global_store_dword v[28:29], v1, off offset:2048
	v_add_f32_e32 v1, v88, v4
	v_sub_f32_e32 v1, v1, v145
	v_min_f32_e32 v28, 0x42a00000, v1
	v_min_f32_e32 v29, 0x42a00000, v2
	v_mul_f32_e32 v28, 0x3fb8aa3b, v28
	v_mul_f32_e32 v29, 0x3fb8aa3b, v29
	v_exp_f32_e32 v28, v28
	v_exp_f32_e32 v29, v29
	v_mul_f32_e32 v1, 0xbfb8aa3b, v1
	v_pk_mul_f32 v[28:29], v[78:79], v[28:29]
	s_nop 0
	v_cvt_pk_bf16_f32 v28, v28, v29
	global_store_dword v[26:27], v28, off
	v_min_f32_e32 v26, 0x42a00000, v5
	v_min_f32_e32 v27, 0x42a00000, v6
	v_mul_f32_e32 v26, 0x3fb8aa3b, v26
	v_mul_f32_e32 v27, 0x3fb8aa3b, v27
	v_exp_f32_e32 v26, v26
	v_exp_f32_e32 v27, v27
	s_nop 0
	v_pk_mul_f32 v[26:27], v[78:79], v[26:27]
	s_nop 0
	v_cvt_pk_bf16_f32 v26, v26, v27
	global_store_dword v[36:37], v26, off
	v_exp_f32_e32 v26, v1
	v_mul_f32_e32 v1, 0xbfb8aa3b, v2
	v_exp_f32_e32 v27, v1
	v_add_f32_e32 v2, v97, v0
	v_sub_f32_e32 v2, v2, v55
	v_pk_mul_f32 v[26:27], v[84:85], v[26:27]
	s_nop 0
	v_cvt_pk_bf16_f32 v1, v26, v27
	global_store_dword v[24:25], v1, off offset:2048
	v_mul_f32_e32 v1, 0xbfb8aa3b, v5
	v_exp_f32_e32 v24, v1
	v_mul_f32_e32 v1, 0xbfb8aa3b, v6
	v_exp_f32_e32 v25, v1
	v_add_f32_e32 v5, v120, v148
	v_add_f32_e32 v6, v121, v146
	v_sub_f32_e32 v5, v5, v3
	v_pk_mul_f32 v[24:25], v[90:91], v[24:25]
	v_sub_f32_e32 v6, v6, v7
	v_cvt_pk_bf16_f32 v1, v24, v25
	global_store_dword v[22:23], v1, off
	v_add_f32_e32 v1, v96, v4
	v_sub_f32_e32 v1, v1, v145
	v_min_f32_e32 v22, 0x42a00000, v1
	v_min_f32_e32 v23, 0x42a00000, v2
	v_mul_f32_e32 v22, 0x3fb8aa3b, v22
	v_mul_f32_e32 v23, 0x3fb8aa3b, v23
	v_exp_f32_e32 v22, v22
	v_exp_f32_e32 v23, v23
	v_mul_f32_e32 v1, 0xbfb8aa3b, v1
	v_pk_mul_f32 v[22:23], v[86:87], v[22:23]
	s_nop 0
	v_cvt_pk_bf16_f32 v22, v22, v23
	global_store_dword v[20:21], v22, off offset:2048
	v_min_f32_e32 v20, 0x42a00000, v5
	v_min_f32_e32 v21, 0x42a00000, v6
	v_mul_f32_e32 v20, 0x3fb8aa3b, v20
	v_mul_f32_e32 v21, 0x3fb8aa3b, v21
	v_exp_f32_e32 v20, v20
	v_exp_f32_e32 v21, v21
	s_nop 0
	v_pk_mul_f32 v[20:21], v[86:87], v[20:21]
	s_nop 0
	v_cvt_pk_bf16_f32 v20, v20, v21
	global_store_dword v[36:37], v20, off offset:2048
	v_exp_f32_e32 v20, v1
	v_mul_f32_e32 v1, 0xbfb8aa3b, v2
	v_exp_f32_e32 v21, v1
	v_add_f32_e32 v2, v107, v0
	v_sub_f32_e32 v2, v2, v55
	v_add_f32_e32 v0, v111, v0
	v_pk_mul_f32 v[20:21], v[92:93], v[20:21]
	s_nop 0
	v_cvt_pk_bf16_f32 v1, v20, v21
	global_store_dword v[16:17], v1, off
	v_mul_f32_e32 v1, 0xbfb8aa3b, v5
	v_exp_f32_e32 v20, v1
	v_mul_f32_e32 v1, 0xbfb8aa3b, v6
	v_exp_f32_e32 v21, v1
	v_add_f32_e32 v5, v118, v148
	v_add_f32_e32 v6, v119, v146
	v_sub_f32_e32 v5, v5, v3
	v_pk_mul_f32 v[20:21], v[98:99], v[20:21]
	v_sub_f32_e32 v6, v6, v7
	v_cvt_pk_bf16_f32 v1, v20, v21
	global_store_dword v[16:17], v1, off offset:2048
	v_add_f32_e32 v1, v106, v4
	v_sub_f32_e32 v1, v1, v145
	v_min_f32_e32 v16, 0x42a00000, v1
	v_min_f32_e32 v17, 0x42a00000, v2
	v_mul_f32_e32 v16, 0x3fb8aa3b, v16
	v_mul_f32_e32 v17, 0x3fb8aa3b, v17
	v_exp_f32_e32 v16, v16
	v_exp_f32_e32 v17, v17
	v_mul_f32_e32 v1, 0xbfb8aa3b, v1
	v_pk_mul_f32 v[16:17], v[94:95], v[16:17]
	s_nop 0
	v_cvt_pk_bf16_f32 v16, v16, v17
	global_store_dword v[18:19], v16, off
	v_min_f32_e32 v16, 0x42a00000, v5
	v_min_f32_e32 v17, 0x42a00000, v6
	v_mul_f32_e32 v16, 0x3fb8aa3b, v16
	v_mul_f32_e32 v17, 0x3fb8aa3b, v17
	v_exp_f32_e32 v16, v16
	v_exp_f32_e32 v17, v17
	s_nop 0
	v_pk_mul_f32 v[16:17], v[94:95], v[16:17]
	s_nop 0
	v_cvt_pk_bf16_f32 v18, v16, v17
	v_add_co_u32_e32 v16, vcc, s63, v48
	s_nop 1
	v_addc_co_u32_e32 v17, vcc, 0, v49, vcc
	global_store_dword v[16:17], v18, off
	v_exp_f32_e32 v18, v1
	v_mul_f32_e32 v1, 0xbfb8aa3b, v2
	v_exp_f32_e32 v19, v1
	s_nop 0
	v_pk_mul_f32 v[18:19], v[100:101], v[18:19]
	s_nop 0
	v_cvt_pk_bf16_f32 v1, v18, v19
	global_store_dword v[14:15], v1, off offset:2048
	v_mul_f32_e32 v1, 0xbfb8aa3b, v5
	v_exp_f32_e32 v14, v1
	v_mul_f32_e32 v1, 0xbfb8aa3b, v6
	v_exp_f32_e32 v15, v1
	s_nop 0
	v_pk_mul_f32 v[14:15], v[104:105], v[14:15]
	s_nop 0
	v_cvt_pk_bf16_f32 v1, v14, v15
	global_store_dword v[12:13], v1, off
	v_add_f32_e32 v1, v110, v4
	v_sub_f32_e32 v4, v0, v55
	v_add_f32_e32 v0, v116, v148
	v_sub_f32_e32 v2, v1, v145
	v_sub_f32_e32 v5, v0, v3
	v_add_f32_e32 v0, v117, v146
	v_sub_f32_e32 v6, v0, v7
	v_min_f32_e32 v0, 0x42a00000, v2
	v_min_f32_e32 v1, 0x42a00000, v4
	v_mul_f32_e32 v0, 0x3fb8aa3b, v0
	v_mul_f32_e32 v1, 0x3fb8aa3b, v1
	v_exp_f32_e32 v0, v0
	v_exp_f32_e32 v1, v1
	s_nop 0
	v_pk_mul_f32 v[0:1], v[102:103], v[0:1]
	s_nop 0
	v_cvt_pk_bf16_f32 v0, v0, v1
	global_store_dword v[10:11], v0, off offset:2048
	v_min_f32_e32 v0, 0x42a00000, v5
	v_min_f32_e32 v1, 0x42a00000, v6
	v_mul_f32_e32 v0, 0x3fb8aa3b, v0
	v_mul_f32_e32 v1, 0x3fb8aa3b, v1
	v_exp_f32_e32 v0, v0
	v_exp_f32_e32 v1, v1
	s_nop 0
	v_pk_mul_f32 v[0:1], v[102:103], v[0:1]
	s_nop 0
	v_cvt_pk_bf16_f32 v0, v0, v1
	global_store_dword v[16:17], v0, off offset:2048
	v_mul_f32_e32 v0, 0xbfb8aa3b, v2
	v_mul_f32_e32 v1, 0xbfb8aa3b, v4
	v_exp_f32_e32 v0, v0
	v_exp_f32_e32 v1, v1
	s_nop 0
	v_pk_mul_f32 v[0:1], v[108:109], v[0:1]
	s_nop 0
	v_cvt_pk_bf16_f32 v0, v0, v1
	global_store_dword v[8:9], v0, off
	v_mul_f32_e32 v0, 0xbfb8aa3b, v5
	v_mul_f32_e32 v1, 0xbfb8aa3b, v6
	v_exp_f32_e32 v0, v0
	v_exp_f32_e32 v1, v1
	s_nop 0
	v_pk_mul_f32 v[0:1], v[112:113], v[0:1]
	s_nop 0
	v_cvt_pk_bf16_f32 v0, v0, v1
	global_store_dword v[8:9], v0, off offset:2048
	s_cbranch_scc1 .LBB0_394
	s_lshl_b32 s12, s56, 1
	s_ashr_i32 s13, s12, 31
	s_lshl_b64 s[12:13], s[12:13], 18
	s_add_u32 s9, s84, s12
	s_addc_u32 s12, s85, s13
	s_lshl_b32 s8, s8, 12
	v_mul_f32_e32 v0, 0x3fb8aa3b, v145
	v_mul_f32_e32 v1, 0x3fb8aa3b, v55
	s_add_u32 s8, s9, s8
	v_exp_f32_e32 v0, v0
	v_exp_f32_e32 v1, v1
	s_addc_u32 s9, s12, 0
	s_add_u32 s8, s8, s0
	s_addc_u32 s9, s9, 0
	global_store_dwordx2 v46, v[0:1], s[8:9]
	v_mul_f32_e32 v0, 0x3fb8aa3b, v3
	v_mul_f32_e32 v1, 0x3fb8aa3b, v7
	v_mov_b32_e32 v47, v129
	v_exp_f32_e32 v0, v0
	v_exp_f32_e32 v1, v1
	v_lshl_add_u64 v[4:5], s[8:9], 0, v[46:47]
	v_add_co_u32_e32 v2, vcc, 0x40000, v4
	s_nop 1
	v_addc_co_u32_e32 v3, vcc, 0, v5, vcc
	global_store_dwordx2 v[2:3], v[0:1], off
	s_branch .LBB0_394
